# P5 residual epilogue: base loads batched 12-20 deep instead of 32 serialized load-store round trips
# baseline (speedup 1.0000x reference)
;     __device__ __forceinline__ void operator()(const f32x4 (&acc)[2][2][4][2], const Unit& u, int wr, int wc, int fr, int fq) const {
;         const int row0 = u.pm * BM + wr * 64 + fr, col0 = u.pn * BM + wc * 32 + 4 * fq;
;         const float* gb = gate + (size_t)(u.pm >> 3) * NIN;
;         f32x4 gv[2][2];
; #pragma unroll
;         for (int bj = 0; bj < 2; ++bj)
; #pragma unroll
;             for (int n = 0; n < 2; ++n) gv[bj][n] = *(const f32x4*)(gb + col0 + bj * HALF + n * 16);
; #pragma unroll
;         for (int ai = 0; ai < 2; ++ai)
; #pragma unroll
;             for (int m = 0; m < 4; ++m) { const size_t off = (size_t)(row0 + ai * HALF + m * 16) * 2048 + col0;
; #pragma unroll
;                 for (int bj = 0; bj < 2; ++bj)
; #pragma unroll
;                     for (int n = 0; n < 2; ++n) { const f32x4 bs = *(const f32x4*)(base + off + bj * HALF + n * 16);
;                         *(f32x4*)(out + off + bj * HALF + n * 16) = bs + gv[bj][n] * acc[ai][bj][m][n]; } }
.LBB0_616:
	v_lshl_add_u32 v178, s38, 8, v158
	v_lshl_or_b32 v176, s55, 8, v160
	s_ashr_i32 s29, s38, 3
	v_ashrrev_i32_e32 v179, 31, v178
	s_mul_hi_i32 s31, s29, 0xc000
	s_mul_i32 s29, s29, 0xc000
	v_ashrrev_i32_e32 v177, 31, v176
	v_lshlrev_b64 v[130:131], 11, v[178:179]
	s_add_u32 s40, s50, s29
	v_lshl_add_u64 v[130:131], v[130:131], 0, v[176:177]
	s_addc_u32 s41, s51, s31
	v_lshlrev_b64 v[156:157], 2, v[130:131]
	v_lshl_add_u64 v[128:129], v[176:177], 2, s[40:41]
	global_load_dwordx4 v[140:143], v[128:129], off
	global_load_dwordx4 v[136:139], v[128:129], off offset:64
	global_load_dwordx4 v[132:135], v[128:129], off offset:512
	s_nop 0
	global_load_dwordx4 v[128:131], v[128:129], off offset:576
	v_add_u32_e32 v192, 0x20000, v156
	v_add_u32_e32 v193, 0x40000, v156
	v_add_u32_e32 v224, 0x60000, v156
	v_add_u32_e32 v225, 0x100000, v156
	v_add_u32_e32 v226, 0x120000, v156
	v_add_u32_e32 v227, 0x140000, v156
	v_add_u32_e32 v228, 0x160000, v156
	s_andn2_b64 vcc, exec, s[4:5]
	s_mov_b64 s[4:5], -1
	global_load_dwordx4 v[172:175], v156, s[6:7]
	global_load_dwordx4 v[176:179], v156, s[6:7] offset:64
	global_load_dwordx4 v[180:183], v156, s[6:7] offset:512
	global_load_dwordx4 v[184:187], v156, s[6:7] offset:576
	global_load_dwordx4 v[188:191], v192, s[6:7]
	global_load_dwordx4 v[196:199], v192, s[6:7] offset:64
	global_load_dwordx4 v[200:203], v192, s[6:7] offset:512
	global_load_dwordx4 v[204:207], v192, s[6:7] offset:576
	global_load_dwordx4 v[208:211], v193, s[6:7]
	global_load_dwordx4 v[212:215], v193, s[6:7] offset:64
	global_load_dwordx4 v[216:219], v193, s[6:7] offset:512
	global_load_dwordx4 v[220:223], v193, s[6:7] offset:576
	s_waitcnt vmcnt(11)
	v_pk_fma_f32 v[126:127], v[126:127], v[142:143], v[174:175]
	v_pk_fma_f32 v[124:125], v[124:125], v[140:141], v[172:173]
	global_store_dwordx4 v156, v[124:127], s[8:9]
	s_waitcnt vmcnt(11)
	v_pk_fma_f32 v[122:123], v[122:123], v[138:139], v[178:179]
	v_pk_fma_f32 v[120:121], v[120:121], v[136:137], v[176:177]
	global_store_dwordx4 v156, v[120:123], s[8:9] offset:64
	s_waitcnt vmcnt(11)
	v_pk_fma_f32 v[118:119], v[118:119], v[134:135], v[182:183]
	v_pk_fma_f32 v[116:117], v[116:117], v[132:133], v[180:181]
	global_store_dwordx4 v156, v[116:119], s[8:9] offset:512
	s_waitcnt vmcnt(11)
	v_pk_fma_f32 v[106:107], v[106:107], v[130:131], v[186:187]
	v_pk_fma_f32 v[104:105], v[104:105], v[128:129], v[184:185]
	global_store_dwordx4 v156, v[104:107], s[8:9] offset:576
	global_load_dwordx4 v[172:175], v224, s[6:7]
	global_load_dwordx4 v[176:179], v224, s[6:7] offset:64
	global_load_dwordx4 v[180:183], v224, s[6:7] offset:512
	global_load_dwordx4 v[184:187], v224, s[6:7] offset:576
	global_load_dwordx4 v[124:127], v225, s[6:7]
	global_load_dwordx4 v[120:123], v225, s[6:7] offset:64
	global_load_dwordx4 v[116:119], v225, s[6:7] offset:512
	global_load_dwordx4 v[104:107], v225, s[6:7] offset:576
	s_waitcnt vmcnt(19)
	v_pk_fma_f32 v[114:115], v[114:115], v[142:143], v[190:191]
	v_pk_fma_f32 v[112:113], v[112:113], v[140:141], v[188:189]
	global_store_dwordx4 v192, v[112:115], s[8:9]
	s_waitcnt vmcnt(19)
	v_pk_fma_f32 v[110:111], v[110:111], v[138:139], v[198:199]
	v_pk_fma_f32 v[108:109], v[108:109], v[136:137], v[196:197]
	global_store_dwordx4 v192, v[108:111], s[8:9] offset:64
	s_waitcnt vmcnt(19)
	v_pk_fma_f32 v[102:103], v[102:103], v[134:135], v[202:203]
	v_pk_fma_f32 v[100:101], v[100:101], v[132:133], v[200:201]
	global_store_dwordx4 v192, v[100:103], s[8:9] offset:512
	s_waitcnt vmcnt(19)
	v_pk_fma_f32 v[90:91], v[90:91], v[130:131], v[206:207]
	v_pk_fma_f32 v[88:89], v[88:89], v[128:129], v[204:205]
	global_store_dwordx4 v192, v[88:91], s[8:9] offset:576
	global_load_dwordx4 v[188:191], v226, s[6:7]
	global_load_dwordx4 v[196:199], v226, s[6:7] offset:64
	global_load_dwordx4 v[200:203], v226, s[6:7] offset:512
	global_load_dwordx4 v[204:207], v226, s[6:7] offset:576
	global_load_dwordx4 v[112:115], v227, s[6:7]
	global_load_dwordx4 v[108:111], v227, s[6:7] offset:64
	global_load_dwordx4 v[100:103], v227, s[6:7] offset:512
	global_load_dwordx4 v[88:91], v227, s[6:7] offset:576
	s_waitcnt vmcnt(27)
	v_pk_fma_f32 v[98:99], v[98:99], v[142:143], v[210:211]
	v_pk_fma_f32 v[96:97], v[96:97], v[140:141], v[208:209]
	global_store_dwordx4 v193, v[96:99], s[8:9]
	s_waitcnt vmcnt(27)
	v_pk_fma_f32 v[94:95], v[94:95], v[138:139], v[214:215]
	v_pk_fma_f32 v[92:93], v[92:93], v[136:137], v[212:213]
	global_store_dwordx4 v193, v[92:95], s[8:9] offset:64
	s_waitcnt vmcnt(27)
; #define PG8_BAR __builtin_amdgcn_s_barrier()
; template <class Epi, class Sched, bool ALIGN_EPI = false, bool SP2 = false>
; __device__ __forceinline__ void gemm_phase(PG8_LAS unsigned char* lds, const Gemm g, const Sched& S, const Epi& E) {
;     ...
;         if constexpr (ALIGN_EPI) { if (wr == 1) PG8_BAR; }
;     __device__ __forceinline__ void operator()(const f32x4 (&acc)[2][2][4][2], const Unit& u, int wr, int wc, int fr, int fq) const {
;     ...
;             for (int m = 0; m < 4; ++m) { const size_t off = (size_t)(row0 + ai * HALF + m * 16) * 2048 + col0;
; #pragma unroll
;                 for (int bj = 0; bj < 2; ++bj)
; #pragma unroll
;                     for (int n = 0; n < 2; ++n) { const f32x4 bs = *(const f32x4*)(base + off + bj * HALF + n * 16);
;                         *(f32x4*)(out + off + bj * HALF + n * 16) = bs + gv[bj][n] * acc[ai][bj][m][n]; } }
	v_pk_fma_f32 v[86:87], v[86:87], v[134:135], v[218:219]
	v_pk_fma_f32 v[84:85], v[84:85], v[132:133], v[216:217]
	global_store_dwordx4 v193, v[84:87], s[8:9] offset:512
	s_waitcnt vmcnt(27)
	v_pk_fma_f32 v[74:75], v[74:75], v[130:131], v[222:223]
	v_pk_fma_f32 v[72:73], v[72:73], v[128:129], v[220:221]
	global_store_dwordx4 v193, v[72:75], s[8:9] offset:576
	global_load_dwordx4 v[208:211], v228, s[6:7]
	global_load_dwordx4 v[212:215], v228, s[6:7] offset:64
	global_load_dwordx4 v[216:219], v228, s[6:7] offset:512
	global_load_dwordx4 v[220:223], v228, s[6:7] offset:576
	s_waitcnt vmcnt(27)
	v_pk_fma_f32 v[82:83], v[82:83], v[142:143], v[174:175]
	v_pk_fma_f32 v[80:81], v[80:81], v[140:141], v[172:173]
	global_store_dwordx4 v224, v[80:83], s[8:9]
	s_waitcnt vmcnt(27)
	v_pk_fma_f32 v[78:79], v[78:79], v[138:139], v[178:179]
	v_pk_fma_f32 v[76:77], v[76:77], v[136:137], v[176:177]
	global_store_dwordx4 v224, v[76:79], s[8:9] offset:64
	s_waitcnt vmcnt(27)
	v_pk_fma_f32 v[70:71], v[70:71], v[134:135], v[182:183]
	v_pk_fma_f32 v[68:69], v[68:69], v[132:133], v[180:181]
	global_store_dwordx4 v224, v[68:71], s[8:9] offset:512
	s_waitcnt vmcnt(27)
	v_pk_fma_f32 v[66:67], v[66:67], v[130:131], v[186:187]
	v_pk_fma_f32 v[64:65], v[64:65], v[128:129], v[184:185]
	global_store_dwordx4 v224, v[64:67], s[8:9] offset:576
	s_waitcnt vmcnt(27)
	v_pk_fma_f32 v[62:63], v[62:63], v[142:143], v[126:127]
	v_pk_fma_f32 v[60:61], v[60:61], v[140:141], v[124:125]
	global_store_dwordx4 v225, v[60:63], s[8:9]
	s_waitcnt vmcnt(27)
	v_pk_fma_f32 v[58:59], v[58:59], v[138:139], v[122:123]
	v_pk_fma_f32 v[56:57], v[56:57], v[136:137], v[120:121]
	global_store_dwordx4 v225, v[56:59], s[8:9] offset:64
	s_waitcnt vmcnt(27)
	v_pk_fma_f32 v[54:55], v[54:55], v[134:135], v[118:119]
	v_pk_fma_f32 v[52:53], v[52:53], v[132:133], v[116:117]
	global_store_dwordx4 v225, v[52:55], s[8:9] offset:512
	s_waitcnt vmcnt(27)
	v_pk_fma_f32 v[42:43], v[42:43], v[130:131], v[106:107]
	v_pk_fma_f32 v[40:41], v[40:41], v[128:129], v[104:105]
	global_store_dwordx4 v225, v[40:43], s[8:9] offset:576
	s_waitcnt vmcnt(23)
	v_pk_fma_f32 v[50:51], v[50:51], v[142:143], v[190:191]
	v_pk_fma_f32 v[48:49], v[48:49], v[140:141], v[188:189]
	global_store_dwordx4 v226, v[48:51], s[8:9]
	s_waitcnt vmcnt(23)
	v_pk_fma_f32 v[46:47], v[46:47], v[138:139], v[198:199]
	v_pk_fma_f32 v[44:45], v[44:45], v[136:137], v[196:197]
	global_store_dwordx4 v226, v[44:47], s[8:9] offset:64
	s_waitcnt vmcnt(23)
	v_pk_fma_f32 v[38:39], v[38:39], v[134:135], v[202:203]
	v_pk_fma_f32 v[36:37], v[36:37], v[132:133], v[200:201]
	global_store_dwordx4 v226, v[36:39], s[8:9] offset:512
	s_waitcnt vmcnt(23)
	v_pk_fma_f32 v[26:27], v[26:27], v[130:131], v[206:207]
	v_pk_fma_f32 v[24:25], v[24:25], v[128:129], v[204:205]
	global_store_dwordx4 v226, v[24:27], s[8:9] offset:576
	s_waitcnt vmcnt(23)
	v_pk_fma_f32 v[34:35], v[34:35], v[142:143], v[114:115]
	v_pk_fma_f32 v[32:33], v[32:33], v[140:141], v[112:113]
	global_store_dwordx4 v227, v[32:35], s[8:9]
	s_waitcnt vmcnt(23)
	v_pk_fma_f32 v[30:31], v[30:31], v[138:139], v[110:111]
	v_pk_fma_f32 v[28:29], v[28:29], v[136:137], v[108:109]
	global_store_dwordx4 v227, v[28:31], s[8:9] offset:64
	s_waitcnt vmcnt(23)
	v_pk_fma_f32 v[22:23], v[22:23], v[134:135], v[102:103]
	v_pk_fma_f32 v[20:21], v[20:21], v[132:133], v[100:101]
	global_store_dwordx4 v227, v[20:23], s[8:9] offset:512
	s_waitcnt vmcnt(23)
	v_pk_fma_f32 v[10:11], v[10:11], v[130:131], v[90:91]
	v_pk_fma_f32 v[8:9], v[8:9], v[128:129], v[88:89]
	global_store_dwordx4 v227, v[8:11], s[8:9] offset:576
	s_waitcnt vmcnt(19)
	v_pk_fma_f32 v[18:19], v[18:19], v[142:143], v[210:211]
	v_pk_fma_f32 v[16:17], v[16:17], v[140:141], v[208:209]
	global_store_dwordx4 v228, v[16:19], s[8:9]
	s_waitcnt vmcnt(19)
	v_pk_fma_f32 v[14:15], v[14:15], v[138:139], v[214:215]
	v_pk_fma_f32 v[12:13], v[12:13], v[136:137], v[212:213]
	global_store_dwordx4 v228, v[12:15], s[8:9] offset:64
	s_waitcnt vmcnt(19)
	v_pk_fma_f32 v[6:7], v[6:7], v[134:135], v[218:219]
	v_pk_fma_f32 v[4:5], v[4:5], v[132:133], v[216:217]
	global_store_dwordx4 v228, v[4:7], s[8:9] offset:512
	s_waitcnt vmcnt(19)
	v_pk_fma_f32 v[2:3], v[2:3], v[130:131], v[222:223]
	v_pk_fma_f32 v[0:1], v[0:1], v[128:129], v[220:221]
	global_store_dwordx4 v228, v[0:3], s[8:9] offset:576
	s_cbranch_vccnz .LBB0_605
	s_andn2_b64 vcc, exec, s[16:17]
	s_cbranch_vccnz .LBB0_604
	s_barrier
	s_branch .LBB0_604
